# single edit edit_attn_waits
# speedup vs baseline: 1.0047x; 1.0047x over previous
.LBB0_720:
	s_bitcmp1_b32 s55, 0
	s_cselect_b32 s4, 0x6000, 0
	v_add_u32_e32 v0, s4, v165
	ds_read_b128 v[114:117], v0
	ds_read_b128 v[118:121], v0 offset:1024
	ds_read_b128 v[122:125], v0 offset:6144
	ds_read_b128 v[126:129], v0 offset:7168
	ds_read_b128 v[130:133], v0 offset:12288
	ds_read_b128 v[134:137], v0 offset:13312
	ds_read_b128 v[138:141], v0 offset:18432
	ds_read_b128 v[142:145], v0 offset:19456
	s_waitcnt lgkmcnt(7)
	v_mfma_f32_16x16x32_bf16 v[190:193], v[114:117], v[42:45], 0
	v_mfma_f32_16x16x32_bf16 v[114:117], v[114:117], v[66:69], 0
	s_waitcnt lgkmcnt(5)
	v_mfma_f32_16x16x32_bf16 v[194:197], v[122:125], v[42:45], 0
	v_mfma_f32_16x16x32_bf16 v[122:125], v[122:125], v[66:69], 0
	s_waitcnt lgkmcnt(3)
	v_mfma_f32_16x16x32_bf16 v[198:201], v[130:133], v[42:45], 0
	v_mfma_f32_16x16x32_bf16 v[130:133], v[130:133], v[66:69], 0
	s_waitcnt lgkmcnt(1)
	v_mfma_f32_16x16x32_bf16 v[202:205], v[138:141], v[42:45], 0
	v_mfma_f32_16x16x32_bf16 v[138:141], v[138:141], v[66:69], 0
	ds_read_b128 v[206:209], v0 offset:2048
	ds_read_b128 v[240:243], v0 offset:8192
	ds_read_b128 v[244:247], v0 offset:14336
	ds_read_b128 v[248:251], v0 offset:20480
	s_waitcnt lgkmcnt(4)
	v_mfma_f32_16x16x32_bf16 v[190:193], v[118:121], v[46:49], v[190:193]
	v_mfma_f32_16x16x32_bf16 v[114:117], v[118:121], v[74:77], v[114:117]
	v_mfma_f32_16x16x32_bf16 v[118:121], v[126:129], v[46:49], v[194:197]
	v_mfma_f32_16x16x32_bf16 v[122:125], v[126:129], v[74:77], v[122:125]
	v_mfma_f32_16x16x32_bf16 v[126:129], v[134:137], v[46:49], v[198:201]
	v_mfma_f32_16x16x32_bf16 v[130:133], v[134:137], v[74:77], v[130:133]
	v_mfma_f32_16x16x32_bf16 v[134:137], v[142:145], v[46:49], v[202:205]
	v_mfma_f32_16x16x32_bf16 v[138:141], v[142:145], v[74:77], v[138:141]
	ds_read_b128 v[142:145], v0 offset:3072
	ds_read_b128 v[194:197], v0 offset:9216
	ds_read_b128 v[198:201], v0 offset:15360
	ds_read_b128 v[202:205], v0 offset:21504
	s_waitcnt lgkmcnt(4)
	v_mfma_f32_16x16x32_bf16 v[114:117], v[206:209], v[78:81], v[114:117]
	v_mfma_f32_16x16x32_bf16 v[118:121], v[240:243], v[50:53], v[118:121]
	v_mfma_f32_16x16x32_bf16 v[122:125], v[240:243], v[78:81], v[122:125]
	v_mfma_f32_16x16x32_bf16 v[126:129], v[244:247], v[50:53], v[126:129]
	v_mfma_f32_16x16x32_bf16 v[130:133], v[244:247], v[78:81], v[130:133]
	v_mfma_f32_16x16x32_bf16 v[134:137], v[248:251], v[50:53], v[134:137]
	v_mfma_f32_16x16x32_bf16 v[138:141], v[248:251], v[78:81], v[138:141]
	v_mfma_f32_16x16x32_bf16 v[190:193], v[206:209], v[50:53], v[190:193]
	ds_read_b128 v[206:209], v0 offset:4096
	ds_read_b128 v[240:243], v0 offset:10240
	ds_read_b128 v[244:247], v0 offset:16384
	ds_read_b128 v[248:251], v0 offset:22528
	s_waitcnt lgkmcnt(4)
	v_mfma_f32_16x16x32_bf16 v[114:117], v[142:145], v[82:85], v[114:117]
	v_mfma_f32_16x16x32_bf16 v[118:121], v[194:197], v[54:57], v[118:121]
	v_mfma_f32_16x16x32_bf16 v[122:125], v[194:197], v[82:85], v[122:125]
	v_mfma_f32_16x16x32_bf16 v[126:129], v[198:201], v[54:57], v[126:129]
	v_mfma_f32_16x16x32_bf16 v[130:133], v[198:201], v[82:85], v[130:133]
	v_mfma_f32_16x16x32_bf16 v[134:137], v[202:205], v[54:57], v[134:137]
	v_mfma_f32_16x16x32_bf16 v[138:141], v[202:205], v[82:85], v[138:141]
	v_mfma_f32_16x16x32_bf16 v[190:193], v[142:145], v[54:57], v[190:193]
	ds_read_b128 v[194:197], v0 offset:5120
	ds_read_b128 v[198:201], v0 offset:11264
	ds_read_b128 v[202:205], v0 offset:17408
	ds_read_b128 v[220:223], v0 offset:23552
	s_waitcnt lgkmcnt(4)
	v_mfma_f32_16x16x32_bf16 v[142:145], v[206:209], v[58:61], v[190:193]
	v_mfma_f32_16x16x32_bf16 v[114:117], v[206:209], v[86:89], v[114:117]
	v_mfma_f32_16x16x32_bf16 v[118:121], v[240:243], v[58:61], v[118:121]
	v_mfma_f32_16x16x32_bf16 v[122:125], v[240:243], v[86:89], v[122:125]
	v_mfma_f32_16x16x32_bf16 v[126:129], v[244:247], v[58:61], v[126:129]
	v_mfma_f32_16x16x32_bf16 v[190:193], v[244:247], v[86:89], v[130:133]
	v_mfma_f32_16x16x32_bf16 v[206:209], v[248:251], v[58:61], v[134:137]
	v_mfma_f32_16x16x32_bf16 v[240:243], v[248:251], v[86:89], v[138:141]
	s_waitcnt lgkmcnt(0)
	v_mfma_f32_16x16x32_bf16 v[142:145], v[194:197], v[62:65], v[142:145]
	v_mfma_f32_16x16x32_bf16 v[134:137], v[194:197], v[94:97], v[114:117]
	v_mfma_f32_16x16x32_bf16 v[138:141], v[198:201], v[62:65], v[118:121]
	v_mfma_f32_16x16x32_bf16 v[130:133], v[198:201], v[94:97], v[122:125]
	v_mfma_f32_16x16x32_bf16 v[118:121], v[202:205], v[62:65], v[126:129]
	v_mfma_f32_16x16x32_bf16 v[126:129], v[202:205], v[94:97], v[190:193]
	v_mfma_f32_16x16x32_bf16 v[114:117], v[220:223], v[62:65], v[206:209]
	v_mfma_f32_16x16x32_bf16 v[122:125], v[220:223], v[94:97], v[240:243]
	s_cmp_lt_u32 s55, s46
	s_cbranch_scc1 .LBB0_722
	v_add_u32_e32 v190, s42, v231
	v_mov_b32_e32 v0, s63
	v_cmp_gt_i32_e32 vcc, v190, v237
	v_cmp_lt_i32_e64 s[4:5], v190, v237
	v_add_u32_e32 v191, 2, v190
	v_cndmask_b32_e32 v0, v142, v0, vcc
	v_cndmask_b32_e64 v142, v0, v142, s[4:5]
	v_cndmask_b32_e64 v143, v224, v143, s[4:5]
	v_cmp_le_i32_e64 s[4:5], v191, v237
	v_add_u32_e32 v192, 3, v190
	v_add_u32_e32 v193, 16, v190
	v_cndmask_b32_e64 v144, v224, v144, s[4:5]
	v_cmp_le_i32_e64 s[4:5], v192, v237
	v_mov_b32_e32 v0, s63
	v_add_u32_e32 v194, 18, v190
	v_cndmask_b32_e64 v145, v224, v145, s[4:5]
	v_cmp_gt_i32_e64 s[4:5], v193, v237
	v_add_u32_e32 v193, 17, v190
	v_add_u32_e32 v195, 19, v190
	v_cndmask_b32_e64 v138, v138, v0, s[4:5]
	v_cmp_le_i32_e64 s[4:5], v193, v237
	v_add_u32_e32 v196, 32, v190
	v_add_u32_e32 v197, 33, v190
	v_cndmask_b32_e64 v139, v224, v139, s[4:5]
	v_cmp_le_i32_e64 s[4:5], v194, v237
	v_add_u32_e32 v198, 34, v190
	v_add_u32_e32 v199, 35, v190
	v_cndmask_b32_e64 v140, v224, v140, s[4:5]
	v_cmp_le_i32_e64 s[4:5], v195, v237
	v_add_u32_e32 v200, 48, v190
	v_add_u32_e32 v201, 49, v190
	v_cndmask_b32_e64 v141, v224, v141, s[4:5]
	v_cmp_gt_i32_e64 s[4:5], v196, v237
	v_add_u32_e32 v202, 50, v190
	v_add_u32_e32 v203, 51, v190
	v_cndmask_b32_e64 v118, v118, v0, s[4:5]
	v_cmp_le_i32_e64 s[4:5], v197, v237
	s_nop 1
	v_cndmask_b32_e64 v119, v224, v119, s[4:5]
	v_cmp_le_i32_e64 s[4:5], v198, v237
	s_nop 1
	v_cndmask_b32_e64 v120, v224, v120, s[4:5]
	v_cmp_le_i32_e64 s[4:5], v199, v237
	s_nop 1
	v_cndmask_b32_e64 v121, v224, v121, s[4:5]
	v_cmp_gt_i32_e64 s[4:5], v200, v237
	s_nop 1
	v_cndmask_b32_e64 v114, v114, v0, s[4:5]
	v_cmp_le_i32_e64 s[4:5], v201, v237
	s_nop 1
	v_cndmask_b32_e64 v115, v224, v115, s[4:5]
	v_cmp_le_i32_e64 s[4:5], v202, v237
	s_nop 1
	v_cndmask_b32_e64 v116, v224, v116, s[4:5]
	v_cmp_le_i32_e64 s[4:5], v203, v237
	s_nop 1
	v_cndmask_b32_e64 v117, v224, v117, s[4:5]
	v_cmp_gt_i32_e64 s[4:5], v190, v238
	s_nop 1
	v_cndmask_b32_e64 v0, v134, v0, s[4:5]
	v_cmp_lt_i32_e64 s[4:5], v190, v238
	s_nop 1
	v_cndmask_b32_e64 v134, v0, v134, s[4:5]
	v_mov_b32_e32 v0, s63
	v_cndmask_b32_e32 v130, v130, v0, vcc
	v_cmp_le_i32_e32 vcc, v193, v238
	v_cndmask_b32_e64 v135, v224, v135, s[4:5]
	v_cmp_le_i32_e64 s[4:5], v191, v238
	v_cndmask_b32_e32 v131, v224, v131, vcc
	v_cmp_le_i32_e32 vcc, v194, v238
	v_cndmask_b32_e64 v136, v224, v136, s[4:5]
	v_cmp_le_i32_e64 s[4:5], v192, v238
	v_cndmask_b32_e32 v132, v224, v132, vcc
	v_cmp_le_i32_e32 vcc, v195, v238
	v_cndmask_b32_e64 v137, v224, v137, s[4:5]
	s_nop 0
	v_cndmask_b32_e32 v133, v224, v133, vcc
	v_cmp_gt_i32_e32 vcc, v196, v238
	s_nop 1
	v_cndmask_b32_e32 v126, v126, v0, vcc
	v_cmp_le_i32_e32 vcc, v197, v238
	s_nop 1
	v_cndmask_b32_e32 v127, v224, v127, vcc
	v_cmp_le_i32_e32 vcc, v198, v238
	s_nop 1
	v_cndmask_b32_e32 v128, v224, v128, vcc
	v_cmp_le_i32_e32 vcc, v199, v238
	s_nop 1
	v_cndmask_b32_e32 v129, v224, v129, vcc
	v_cmp_gt_i32_e32 vcc, v200, v238
	s_nop 1
	v_cndmask_b32_e32 v122, v122, v0, vcc
	v_cmp_le_i32_e32 vcc, v201, v238
	s_nop 1
	v_cndmask_b32_e32 v123, v224, v123, vcc
	v_cmp_le_i32_e32 vcc, v202, v238
	s_nop 1
	v_cndmask_b32_e32 v124, v224, v124, vcc
	v_cmp_le_i32_e32 vcc, v203, v238
	s_nop 1
	v_cndmask_b32_e32 v125, v224, v125, vcc
.LBB0_722:
	v_max3_f32 v0, v142, s63, v143
	v_max3_f32 v0, v0, v144, v145
	v_max3_f32 v0, v0, v138, v139
	v_max3_f32 v0, v0, v140, v141
	v_max3_f32 v0, v0, v118, v119
	v_max3_f32 v0, v0, v120, v121
	v_max3_f32 v0, v0, v114, v115
	v_max3_f32 v0, v0, v116, v117
	ds_bpermute_b32 v190, v232, v0
	s_andn2_b64 vcc, exec, s[6:7]
	s_waitcnt lgkmcnt(0)
	v_max_f32_e32 v190, v190, v190
	v_max_f32_e32 v0, v0, v190
	ds_bpermute_b32 v190, v233, v0
	s_waitcnt lgkmcnt(0)
	v_max3_f32 v239, v189, v0, v190
	v_sub_f32_e32 v138, v138, v239
	v_exp_f32_e32 v203, v138
	v_sub_f32_e32 v138, v139, v239
	v_exp_f32_e32 v201, v138
	v_sub_f32_e32 v138, v140, v239
	v_sub_f32_e32 v114, v114, v239
	v_exp_f32_e32 v199, v138
	v_sub_f32_e32 v138, v141, v239
	v_exp_f32_e32 v141, v114
	v_sub_f32_e32 v114, v115, v239
	v_exp_f32_e32 v139, v114
	v_sub_f32_e32 v114, v116, v239
	v_sub_f32_e32 v0, v189, v239
	v_sub_f32_e32 v143, v143, v239
	v_exp_f32_e32 v189, v114
	v_sub_f32_e32 v114, v117, v239
	v_exp_f32_e32 v209, v143
	v_exp_f32_e32 v143, v114
	v_max3_f32 v114, v134, s63, v135
	v_max3_f32 v114, v114, v136, v137
	v_max3_f32 v114, v114, v130, v131
	v_sub_f32_e32 v118, v118, v239
	v_max3_f32 v114, v114, v132, v133
	v_exp_f32_e32 v195, v118
	v_sub_f32_e32 v118, v119, v239
	v_max3_f32 v114, v114, v126, v127
	v_exp_f32_e32 v193, v118
	v_sub_f32_e32 v118, v120, v239
	v_max3_f32 v114, v114, v128, v129
	v_sub_f32_e32 v145, v145, v239
	v_exp_f32_e32 v191, v118
	v_sub_f32_e32 v118, v121, v239
	v_max3_f32 v114, v114, v122, v123
	v_exp_f32_e32 v205, v145
	v_exp_f32_e32 v145, v118
	v_max3_f32 v118, v114, v124, v125
	ds_bpermute_b32 v119, v232, v118
	v_exp_f32_e32 v197, v138
	v_sub_f32_e32 v142, v142, v239
	v_exp_f32_e32 v211, v142
	v_sub_f32_e32 v144, v144, v239
	s_waitcnt lgkmcnt(0)
	v_max_f32_e32 v119, v119, v119
	v_max_f32_e32 v138, v118, v119
	ds_bpermute_b32 v140, v233, v138
	v_exp_f32_e32 v0, v0
	v_exp_f32_e32 v207, v144
	v_cvt_pk_bf16_f32 v114, v211, v209
	v_cvt_pk_bf16_f32 v115, v207, v205
	s_waitcnt lgkmcnt(0)
	v_max3_f32 v240, v188, v138, v140
	v_sub_f32_e32 v130, v130, v240
	v_sub_f32_e32 v134, v134, v240
	v_exp_f32_e32 v202, v130
	v_sub_f32_e32 v130, v131, v240
	v_sub_f32_e32 v126, v126, v240
	v_sub_f32_e32 v122, v122, v240
	v_exp_f32_e32 v210, v134
	v_sub_f32_e32 v134, v135, v240
	v_exp_f32_e32 v200, v130
	v_sub_f32_e32 v130, v132, v240
	v_exp_f32_e32 v194, v126
	v_sub_f32_e32 v126, v127, v240
	v_exp_f32_e32 v140, v122
	v_sub_f32_e32 v122, v123, v240
	v_sub_f32_e32 v142, v188, v240
	v_exp_f32_e32 v208, v134
	v_sub_f32_e32 v134, v136, v240
	v_exp_f32_e32 v198, v130
	v_sub_f32_e32 v130, v133, v240
	v_exp_f32_e32 v192, v126
	v_sub_f32_e32 v126, v128, v240
	v_exp_f32_e32 v138, v122
	v_sub_f32_e32 v122, v124, v240
	v_exp_f32_e32 v206, v134
	v_sub_f32_e32 v134, v137, v240
	v_exp_f32_e32 v196, v130
	v_exp_f32_e32 v190, v126
	v_sub_f32_e32 v126, v129, v240
	v_exp_f32_e32 v130, v142
	v_exp_f32_e32 v188, v122
	v_sub_f32_e32 v122, v125, v240
	v_exp_f32_e32 v204, v134
	v_exp_f32_e32 v144, v126
	v_exp_f32_e32 v142, v122
	v_pk_mul_f32 v[112:113], v[112:113], v[0:1] op_sel_hi:[1,0]
	v_pk_mul_f32 v[110:111], v[110:111], v[0:1] op_sel_hi:[1,0]
	v_pk_mul_f32 v[108:109], v[108:109], v[0:1] op_sel_hi:[1,0]
	v_pk_mul_f32 v[106:107], v[106:107], v[0:1] op_sel_hi:[1,0]
	v_pk_mul_f32 v[104:105], v[104:105], v[0:1] op_sel_hi:[1,0]
	v_pk_mul_f32 v[102:103], v[102:103], v[0:1] op_sel_hi:[1,0]
	v_pk_mul_f32 v[100:101], v[100:101], v[0:1] op_sel_hi:[1,0]
	v_pk_mul_f32 v[98:99], v[98:99], v[0:1] op_sel_hi:[1,0]
	v_pk_mul_f32 v[92:93], v[92:93], v[0:1] op_sel_hi:[1,0]
	v_pk_mul_f32 v[90:91], v[90:91], v[0:1] op_sel_hi:[1,0]
	v_pk_mul_f32 v[72:73], v[72:73], v[0:1] op_sel_hi:[1,0]
	v_pk_mul_f32 v[70:71], v[70:71], v[0:1] op_sel_hi:[1,0]
	v_pk_mul_f32 v[40:41], v[40:41], v[0:1] op_sel_hi:[1,0]
	v_pk_mul_f32 v[38:39], v[38:39], v[0:1] op_sel_hi:[1,0]
	v_pk_mul_f32 v[36:37], v[36:37], v[0:1] op_sel_hi:[1,0]
	v_pk_mul_f32 v[34:35], v[34:35], v[0:1] op_sel_hi:[1,0]
	v_pk_mul_f32 v[32:33], v[32:33], v[130:131] op_sel_hi:[1,0]
	v_pk_mul_f32 v[30:31], v[30:31], v[130:131] op_sel_hi:[1,0]
	v_pk_mul_f32 v[28:29], v[28:29], v[130:131] op_sel_hi:[1,0]
	v_pk_mul_f32 v[26:27], v[26:27], v[130:131] op_sel_hi:[1,0]
	v_pk_mul_f32 v[24:25], v[24:25], v[130:131] op_sel_hi:[1,0]
	v_pk_mul_f32 v[22:23], v[22:23], v[130:131] op_sel_hi:[1,0]
	v_pk_mul_f32 v[20:21], v[20:21], v[130:131] op_sel_hi:[1,0]
	v_pk_mul_f32 v[18:19], v[18:19], v[130:131] op_sel_hi:[1,0]
	v_pk_mul_f32 v[16:17], v[16:17], v[130:131] op_sel_hi:[1,0]
	v_pk_mul_f32 v[14:15], v[14:15], v[130:131] op_sel_hi:[1,0]
	v_pk_mul_f32 v[12:13], v[12:13], v[130:131] op_sel_hi:[1,0]
	v_pk_mul_f32 v[10:11], v[10:11], v[130:131] op_sel_hi:[1,0]
	v_pk_mul_f32 v[8:9], v[8:9], v[130:131] op_sel_hi:[1,0]
	v_pk_mul_f32 v[6:7], v[6:7], v[130:131] op_sel_hi:[1,0]
	v_pk_mul_f32 v[4:5], v[4:5], v[130:131] op_sel_hi:[1,0]
	v_pk_mul_f32 v[2:3], v[2:3], v[130:131] op_sel_hi:[1,0]
	v_cvt_pk_bf16_f32 v116, v203, v201
	v_cvt_pk_bf16_f32 v117, v199, v197
	v_cvt_pk_bf16_f32 v118, v195, v193
	v_cvt_pk_bf16_f32 v119, v191, v145
	v_cvt_pk_bf16_f32 v120, v141, v139
	v_cvt_pk_bf16_f32 v121, v189, v143
	v_cvt_pk_bf16_f32 v122, v210, v208
	v_cvt_pk_bf16_f32 v123, v206, v204
	v_cvt_pk_bf16_f32 v124, v202, v200
	v_cvt_pk_bf16_f32 v125, v198, v196
	v_cvt_pk_bf16_f32 v126, v194, v192
	v_cvt_pk_bf16_f32 v127, v190, v144
	v_cvt_pk_bf16_f32 v128, v140, v138
	v_cvt_pk_bf16_f32 v129, v188, v142
	s_cbranch_vccnz .LBB0_727
	v_add_u32_e32 v131, s54, v160
	ds_read_b128 v[132:135], v131 offset:49152
	ds_read_b128 v[220:223], v131 offset:50176
	ds_read_b128 v[242:245], v131 offset:51200
	ds_read_b128 v[246:249], v131 offset:52224
	s_waitcnt lgkmcnt(3)
	v_mfma_f32_16x16x32_bf16 v[110:113], v[132:135], v[114:117], v[110:113]
	v_mfma_f32_16x16x32_bf16 v[30:33], v[132:135], v[122:125], v[30:33]
	s_waitcnt lgkmcnt(2)
	v_mfma_f32_16x16x32_bf16 v[110:113], v[220:223], v[118:121], v[110:113]
	v_mfma_f32_16x16x32_bf16 v[30:33], v[220:223], v[126:129], v[30:33]
	ds_read_b128 v[132:135], v131 offset:53248
	ds_read_b128 v[220:223], v131 offset:54272
	s_waitcnt lgkmcnt(2)
	v_mfma_f32_16x16x32_bf16 v[106:109], v[242:245], v[114:117], v[106:109]
	v_mfma_f32_16x16x32_bf16 v[26:29], v[242:245], v[122:125], v[26:29]
	v_mfma_f32_16x16x32_bf16 v[106:109], v[246:249], v[118:121], v[106:109]
	v_mfma_f32_16x16x32_bf16 v[26:29], v[246:249], v[126:129], v[26:29]
	ds_read_b128 v[242:245], v131 offset:55296
	ds_read_b128 v[246:249], v131 offset:56320
	s_waitcnt lgkmcnt(2)
	v_mfma_f32_16x16x32_bf16 v[102:105], v[132:135], v[114:117], v[102:105]
	v_mfma_f32_16x16x32_bf16 v[22:25], v[132:135], v[122:125], v[22:25]
	v_mfma_f32_16x16x32_bf16 v[102:105], v[220:223], v[118:121], v[102:105]
	v_mfma_f32_16x16x32_bf16 v[22:25], v[220:223], v[126:129], v[22:25]
	ds_read_b128 v[132:135], v131 offset:57344
	ds_read_b128 v[220:223], v131 offset:58368
	s_waitcnt lgkmcnt(2)
	v_mfma_f32_16x16x32_bf16 v[98:101], v[242:245], v[114:117], v[98:101]
	v_mfma_f32_16x16x32_bf16 v[18:21], v[242:245], v[122:125], v[18:21]
	v_mfma_f32_16x16x32_bf16 v[98:101], v[246:249], v[118:121], v[98:101]
	v_mfma_f32_16x16x32_bf16 v[18:21], v[246:249], v[126:129], v[18:21]
	ds_read_b128 v[242:245], v131 offset:59392
	ds_read_b128 v[246:249], v131 offset:60416
	s_waitcnt lgkmcnt(2)
	v_mfma_f32_16x16x32_bf16 v[90:93], v[132:135], v[114:117], v[90:93]
	v_mfma_f32_16x16x32_bf16 v[14:17], v[132:135], v[122:125], v[14:17]
	v_mfma_f32_16x16x32_bf16 v[90:93], v[220:223], v[118:121], v[90:93]
	v_mfma_f32_16x16x32_bf16 v[14:17], v[220:223], v[126:129], v[14:17]
	ds_read_b128 v[132:135], v131 offset:61440
	ds_read_b128 v[220:223], v131 offset:62464
	s_waitcnt lgkmcnt(2)
	v_mfma_f32_16x16x32_bf16 v[70:73], v[242:245], v[114:117], v[70:73]
	v_mfma_f32_16x16x32_bf16 v[10:13], v[242:245], v[122:125], v[10:13]
	v_mfma_f32_16x16x32_bf16 v[70:73], v[246:249], v[118:121], v[70:73]
	v_mfma_f32_16x16x32_bf16 v[10:13], v[246:249], v[126:129], v[10:13]
	ds_read_b128 v[242:245], v131 offset:63488
	ds_read_b128 v[246:249], v131 offset:64512
	s_waitcnt lgkmcnt(2)
	v_mfma_f32_16x16x32_bf16 v[38:41], v[132:135], v[114:117], v[38:41]
	v_mfma_f32_16x16x32_bf16 v[6:9], v[132:135], v[122:125], v[6:9]
	v_mfma_f32_16x16x32_bf16 v[38:41], v[220:223], v[118:121], v[38:41]
	v_mfma_f32_16x16x32_bf16 v[6:9], v[220:223], v[126:129], v[6:9]
	s_waitcnt lgkmcnt(0)
	v_mfma_f32_16x16x32_bf16 v[34:37], v[242:245], v[114:117], v[34:37]
	v_mfma_f32_16x16x32_bf16 v[2:5], v[242:245], v[122:125], v[2:5]
	v_mfma_f32_16x16x32_bf16 v[34:37], v[246:249], v[118:121], v[34:37]
	v_mfma_f32_16x16x32_bf16 v[2:5], v[246:249], v[126:129], v[2:5]
	s_mov_b64 s[4:5], 0
	s_branch .LBB0_728

.LBB0_725:
	v_lshl_add_u32 v0, s52, 14, v234
	ds_read_b128 v[130:133], v0 offset:49152
	ds_read_b128 v[134:137], v0 offset:50176
	ds_read_b128 v[138:141], v0 offset:51200
	ds_read_b128 v[142:145], v0 offset:52224
	s_waitcnt lgkmcnt(3)
	v_mfma_f32_16x16x32_bf16 v[110:113], v[130:133], v[114:117], v[110:113]
	v_mfma_f32_16x16x32_bf16 v[30:33], v[130:133], v[122:125], v[30:33]
	s_waitcnt lgkmcnt(2)
	v_mfma_f32_16x16x32_bf16 v[110:113], v[134:137], v[118:121], v[110:113]
	v_mfma_f32_16x16x32_bf16 v[30:33], v[134:137], v[126:129], v[30:33]
	ds_read_b128 v[130:133], v0 offset:53248
	ds_read_b128 v[134:137], v0 offset:54272
	s_waitcnt lgkmcnt(2)
	v_mfma_f32_16x16x32_bf16 v[106:109], v[138:141], v[114:117], v[106:109]
	v_mfma_f32_16x16x32_bf16 v[26:29], v[138:141], v[122:125], v[26:29]
	v_mfma_f32_16x16x32_bf16 v[106:109], v[142:145], v[118:121], v[106:109]
	v_mfma_f32_16x16x32_bf16 v[26:29], v[142:145], v[126:129], v[26:29]
	ds_read_b128 v[138:141], v0 offset:55296
	ds_read_b128 v[142:145], v0 offset:56320
	s_waitcnt lgkmcnt(2)
	v_mfma_f32_16x16x32_bf16 v[102:105], v[130:133], v[114:117], v[102:105]
	v_mfma_f32_16x16x32_bf16 v[22:25], v[130:133], v[122:125], v[22:25]
	v_mfma_f32_16x16x32_bf16 v[102:105], v[134:137], v[118:121], v[102:105]
	v_mfma_f32_16x16x32_bf16 v[22:25], v[134:137], v[126:129], v[22:25]
	ds_read_b128 v[130:133], v0 offset:57344
	ds_read_b128 v[134:137], v0 offset:58368
	s_waitcnt lgkmcnt(2)
	v_mfma_f32_16x16x32_bf16 v[98:101], v[138:141], v[114:117], v[98:101]
	v_mfma_f32_16x16x32_bf16 v[18:21], v[138:141], v[122:125], v[18:21]
	v_mfma_f32_16x16x32_bf16 v[98:101], v[142:145], v[118:121], v[98:101]
	v_mfma_f32_16x16x32_bf16 v[18:21], v[142:145], v[126:129], v[18:21]
	ds_read_b128 v[138:141], v0 offset:59392
	ds_read_b128 v[142:145], v0 offset:60416
	s_waitcnt lgkmcnt(2)
	v_mfma_f32_16x16x32_bf16 v[90:93], v[130:133], v[114:117], v[90:93]
	v_mfma_f32_16x16x32_bf16 v[14:17], v[130:133], v[122:125], v[14:17]
	v_mfma_f32_16x16x32_bf16 v[90:93], v[134:137], v[118:121], v[90:93]
	v_mfma_f32_16x16x32_bf16 v[14:17], v[134:137], v[126:129], v[14:17]
	ds_read_b128 v[130:133], v0 offset:61440
	ds_read_b128 v[134:137], v0 offset:62464
	s_waitcnt lgkmcnt(2)
	v_mfma_f32_16x16x32_bf16 v[70:73], v[138:141], v[114:117], v[70:73]
	v_mfma_f32_16x16x32_bf16 v[10:13], v[138:141], v[122:125], v[10:13]
	v_mfma_f32_16x16x32_bf16 v[70:73], v[142:145], v[118:121], v[70:73]
	v_mfma_f32_16x16x32_bf16 v[10:13], v[142:145], v[126:129], v[10:13]
	ds_read_b128 v[138:141], v0 offset:63488
	ds_read_b128 v[142:145], v0 offset:64512
	s_waitcnt lgkmcnt(2)
	v_mfma_f32_16x16x32_bf16 v[38:41], v[130:133], v[114:117], v[38:41]
	v_mfma_f32_16x16x32_bf16 v[6:9], v[130:133], v[122:125], v[6:9]
	v_mfma_f32_16x16x32_bf16 v[38:41], v[134:137], v[118:121], v[38:41]
	v_mfma_f32_16x16x32_bf16 v[6:9], v[134:137], v[126:129], v[6:9]
	s_waitcnt lgkmcnt(0)
	v_mfma_f32_16x16x32_bf16 v[34:37], v[138:141], v[114:117], v[34:37]
	v_mfma_f32_16x16x32_bf16 v[2:5], v[138:141], v[122:125], v[2:5]
	v_mfma_f32_16x16x32_bf16 v[34:37], v[142:145], v[118:121], v[34:37]
	v_mfma_f32_16x16x32_bf16 v[2:5], v[142:145], v[126:129], v[2:5]
	s_lshl_b32 s4, s47, 14
	s_add_i32 s54, s4, 0
	s_cmp_gt_i32 s42, s45
	s_cbranch_scc0 .LBB0_720
